# NSA selected loop: in-place PV accumulation + V fragment reads up front (copy block removed); phase H epilogue staged through LDS with full-row dwordx4 stores
# speedup vs baseline: 1.0291x; 1.0291x over previous
; template <bool MASKED, class MaskF>
; DI void flash_pv3(const u16* sV, const f32x4 (&s)[2][4], f32x4 (&O)[2][4], float (&l)[2], MaskF ok, int lane) {
;     ...
;     for (int kt = 0; kt < 4; ++kt)
; #pragma unroll
;       for (int i = 0; i < 4; ++i) {
;         float pv = __builtin_amdgcn_exp2f(s[qt][kt][i]);
;         if (MASKED) pv = ok(kt, i) ? pv : 0.f;
;         pr[kt][i] = pv;
;         rs += pv;
;       }
; DI void nsa_item(int wv0, PP p, int item, unsigned char* smem) {
;     ...
;         if (bit128(wlo, whi, jc)) {
;           if (jc == i) {
;             const bool sel = bit128(mlo, mhi, jc);
;             auto ok = [&](int kt, int ii) { return sel && (16 * kt + 4 * lg + ii) <= qloc; };
;             flash_pv3<true>(sV + bc * 9216, sc_, O, l, ok, lane);
;           } else {
;             flash_pv3<false>(sV + bc * 9216, sc_, O, l, nomask, lane);
;           }
.LBB0_882:
	v_sub_co_u32_e64 v196, s[36:37], s85, 64
	v_lshrrev_b64 v[2:3], s85, v[130:131]
	v_lshrrev_b64 v[166:167], v196, v[134:135]
	v_cndmask_b32_e64 v0, v166, v2, s[36:37]
	v_and_b32_e32 v0, 1, v0
	v_cmp_eq_u64_e32 vcc, 0, v[0:1]
	s_cbranch_vccnz .LBB0_888
	v_exp_f32_e32 v197, v98
	v_exp_f32_e32 v195, v99
	v_exp_f32_e32 v194, v100
	v_exp_f32_e32 v193, v101
	v_exp_f32_e32 v192, v102
	v_exp_f32_e32 v191, v103
	v_exp_f32_e32 v190, v104
	v_exp_f32_e32 v189, v105
	v_exp_f32_e32 v188, v118
	v_exp_f32_e32 v187, v119
	v_exp_f32_e32 v186, v120
	v_exp_f32_e32 v185, v121
	v_exp_f32_e32 v184, v122
	v_exp_f32_e32 v183, v123
	v_exp_f32_e32 v182, v124
	v_exp_f32_e32 v181, v125
	v_exp_f32_e32 v179, v126
	v_exp_f32_e32 v180, v127
	v_exp_f32_e32 v165, v128
	v_exp_f32_e32 v166, v129
	v_exp_f32_e32 v167, v114
	v_exp_f32_e32 v168, v115
	v_exp_f32_e32 v169, v116
	v_exp_f32_e32 v170, v117
	v_exp_f32_e32 v171, v110
	v_exp_f32_e32 v172, v111
	v_exp_f32_e32 v173, v112
	v_exp_f32_e32 v174, v113
	v_exp_f32_e32 v175, v106
	v_exp_f32_e32 v176, v107
	v_exp_f32_e32 v177, v108
	v_exp_f32_e32 v178, v109
	s_cmp_lg_u32 s85, s33
	s_mulk_i32 s45, 0x4800
	v_lshlrev_b32_e32 v160, 1, v28
	v_lshlrev_b32_e32 v3, 1, v164
	s_cbranch_scc1 .Lmy_sel_pv
	s_nop 3
	v_lshrrev_b64 v[98:99], s85, v[20:21]
	v_lshrrev_b64 v[100:101], v196, v[22:23]
	v_cndmask_b32_e64 v0, v100, v98, s[36:37]
	v_and_b32_e32 v0, 1, v0
	v_cmp_eq_u64_e32 vcc, 0, v[0:1]
	s_or_b64 s[40:41], vcc, s[2:3]
	s_or_b64 s[46:47], vcc, s[6:7]
	s_or_b64 s[48:49], vcc, s[8:9]
	s_or_b64 s[50:51], vcc, s[10:11]
	s_or_b64 s[52:53], vcc, s[12:13]
	s_or_b64 s[54:55], vcc, s[14:15]
	s_or_b64 s[56:57], vcc, s[16:17]
	s_or_b64 s[58:59], vcc, s[18:19]
	s_or_b64 s[60:61], vcc, s[20:21]
	s_or_b64 s[62:63], vcc, s[22:23]
	s_or_b64 s[64:65], vcc, s[24:25]
	s_or_b64 s[66:67], vcc, s[26:27]
	s_or_b64 s[74:75], vcc, s[28:29]
	s_or_b64 s[80:81], vcc, s[30:31]
	s_or_b64 s[96:97], vcc, s[34:35]
	v_cndmask_b32_e64 v197, v197, 0, s[40:41]
	v_cndmask_b32_e64 v179, v179, 0, s[40:41]
	v_cndmask_b32_e64 v195, 0, v195, s[4:5]
	v_cndmask_b32_e64 v180, 0, v180, s[4:5]
	v_cndmask_b32_e64 v195, v195, 0, vcc
	v_cndmask_b32_e64 v180, v180, 0, vcc
	v_cndmask_b32_e64 v194, v194, 0, s[46:47]
	v_cndmask_b32_e64 v165, v165, 0, s[46:47]
	v_cndmask_b32_e64 v193, v193, 0, s[48:49]
	v_cndmask_b32_e64 v166, v166, 0, s[48:49]
	v_cndmask_b32_e64 v192, v192, 0, s[50:51]
	v_cndmask_b32_e64 v167, v167, 0, s[50:51]
	v_cndmask_b32_e64 v191, v191, 0, s[52:53]
	v_cndmask_b32_e64 v168, v168, 0, s[52:53]
	v_cndmask_b32_e64 v190, v190, 0, s[54:55]
	v_cndmask_b32_e64 v169, v169, 0, s[54:55]
	v_cndmask_b32_e64 v189, v189, 0, s[56:57]
	v_cndmask_b32_e64 v170, v170, 0, s[56:57]
	v_cndmask_b32_e64 v188, v188, 0, s[58:59]
	v_cndmask_b32_e64 v171, v171, 0, s[58:59]
	v_cndmask_b32_e64 v187, v187, 0, s[60:61]
	v_cndmask_b32_e64 v172, v172, 0, s[60:61]
	v_cndmask_b32_e64 v186, v186, 0, s[62:63]
	v_cndmask_b32_e64 v173, v173, 0, s[62:63]
	v_cndmask_b32_e64 v185, v185, 0, s[64:65]
	v_cndmask_b32_e64 v174, v174, 0, s[64:65]
	v_cndmask_b32_e64 v184, v184, 0, s[66:67]
	v_cndmask_b32_e64 v175, v175, 0, s[66:67]
	v_cndmask_b32_e64 v183, v183, 0, s[74:75]
	v_cndmask_b32_e64 v176, v176, 0, s[74:75]
	v_cndmask_b32_e64 v182, v182, 0, s[80:81]
	v_cndmask_b32_e64 v177, v177, 0, s[80:81]
	v_cndmask_b32_e64 v181, v181, 0, s[96:97]
	v_cndmask_b32_e64 v178, v178, 0, s[96:97]
; DI f32x4 mfma16(bf16x8 a, bf16x8 b, f32x4 c) { return __builtin_amdgcn_mfma_f32_16x16x32_bf16(a, b, c, 0, 0, 0); }
; template <bool MASKED, class MaskF>
; DI void flash_pv3(const u16* sV, const f32x4 (&s)[2][4], f32x4 (&O)[2][4], float (&l)[2], MaskF ok, int lane) {
;     ...
;     l[qt] += rs;
; #pragma unroll
;     for (int ks2 = 0; ks2 < 2; ++ks2) {
;       pf[qt][ks2].u[0] = pk2(pr[2 * ks2][0], pr[2 * ks2][1]);
;       pf[qt][ks2].u[1] = pk2(pr[2 * ks2][2], pr[2 * ks2][3]);
;       pf[qt][ks2].u[2] = pk2(pr[2 * ks2 + 1][0], pr[2 * ks2 + 1][1]);
;       pf[qt][ks2].u[3] = pk2(pr[2 * ks2 + 1][2], pr[2 * ks2 + 1][3]);
;     }
;   }
; #pragma unroll
;   for (int ks2 = 0; ks2 < 2; ++ks2) {
; #pragma unroll
;     for (int dt = 0; dt < 4; ++dt) {
;       union { uint2 h[2]; bf16x8 v; } vf;
;       vf.h[0] = *(const uint2*)(sV + (16 * dt + l15) * 72 + 32 * ks2 + 4 * lg);
;       vf.h[1] = *(const uint2*)(sV + (16 * dt + l15) * 72 + 32 * ks2 + 16 + 4 * lg);
;       O[0][dt] = mfma16(vf.v, pf[0][ks2].v, O[0][dt]);
;       O[1][dt] = mfma16(vf.v, pf[1][ks2].v, O[1][dt]);
;     }
;   }
.Lmy_sel_pv:
	s_add_i32 s40, s45, 32
	v_add3_u32 v198, s40, v160, v159
	v_add3_u32 v206, s40, v3, v159
	v_add_u32_e32 v214, 0x2000, v198
	v_add_u32_e32 v215, 0x2800, v198
	v_add_u32_e32 v216, 0x3000, v198
	v_add_u32_e32 v217, 0x2000, v206
	ds_read2_b64 v[114:117], v214 offset0:128 offset1:132
	ds_read2_b64 v[122:125], v215 offset0:160 offset1:164
	ds_read2_b64 v[198:201], v216 offset0:192 offset1:196
	ds_read2_b64 v[206:209], v217 offset0:128 offset1:132
	ds_read2_b64 v[118:121], v214 offset0:136 offset1:140
	ds_read2_b64 v[126:129], v215 offset0:168 offset1:172
	ds_read2_b64 v[202:205], v216 offset0:200 offset1:204
	ds_read2_b64 v[210:213], v217 offset0:136 offset1:140
	v_cvt_pk_bf16_f32 v106, v197, v195
	v_cvt_pk_bf16_f32 v107, v194, v193
	v_cvt_pk_bf16_f32 v108, v192, v191
	v_cvt_pk_bf16_f32 v109, v190, v189
	v_cvt_pk_bf16_f32 v110, v179, v180
	v_cvt_pk_bf16_f32 v111, v165, v166
	v_cvt_pk_bf16_f32 v112, v167, v168
	v_cvt_pk_bf16_f32 v113, v169, v170
	v_cvt_pk_bf16_f32 v98, v188, v187
	v_cvt_pk_bf16_f32 v99, v186, v185
	v_cvt_pk_bf16_f32 v100, v184, v183
	v_cvt_pk_bf16_f32 v101, v182, v181
	v_cvt_pk_bf16_f32 v102, v171, v172
	v_cvt_pk_bf16_f32 v103, v173, v174
	v_cvt_pk_bf16_f32 v104, v175, v176
	v_cvt_pk_bf16_f32 v105, v177, v178
	s_waitcnt lgkmcnt(7)
	v_mfma_f32_16x16x32_bf16 v[58:61], v[114:117], v[106:109], v[58:61]
	v_add_f32_e32 v0, 0, v197
	v_add_f32_e32 v2, 0, v179
	v_mfma_f32_16x16x32_bf16 v[42:45], v[114:117], v[110:113], v[42:45]
	v_add_f32_e32 v0, v195, v0
	v_add_f32_e32 v2, v180, v2
	s_waitcnt lgkmcnt(6)
	v_mfma_f32_16x16x32_bf16 v[54:57], v[122:125], v[106:109], v[54:57]
	v_add_f32_e32 v0, v194, v0
	v_add_f32_e32 v2, v165, v2
	v_mfma_f32_16x16x32_bf16 v[38:41], v[122:125], v[110:113], v[38:41]
	v_add_f32_e32 v0, v193, v0
	v_add_f32_e32 v2, v166, v2
	s_waitcnt lgkmcnt(5)
	v_mfma_f32_16x16x32_bf16 v[50:53], v[198:201], v[106:109], v[50:53]
	v_add_f32_e32 v0, v192, v0
	v_add_f32_e32 v2, v167, v2
	v_mfma_f32_16x16x32_bf16 v[34:37], v[198:201], v[110:113], v[34:37]
	v_add_f32_e32 v0, v191, v0
	v_add_f32_e32 v2, v168, v2
	s_waitcnt lgkmcnt(4)
	v_mfma_f32_16x16x32_bf16 v[46:49], v[206:209], v[106:109], v[46:49]
	v_add_f32_e32 v0, v190, v0
	v_add_f32_e32 v2, v169, v2
	v_mfma_f32_16x16x32_bf16 v[30:33], v[206:209], v[110:113], v[30:33]
	v_add_f32_e32 v0, v189, v0
	v_add_f32_e32 v2, v170, v2
	s_waitcnt lgkmcnt(3)
	v_mfma_f32_16x16x32_bf16 v[58:61], v[118:121], v[98:101], v[58:61]
	v_add_f32_e32 v0, v188, v0
	v_add_f32_e32 v2, v171, v2
	v_mfma_f32_16x16x32_bf16 v[42:45], v[118:121], v[102:105], v[42:45]
	v_add_f32_e32 v0, v187, v0
	v_add_f32_e32 v2, v172, v2
	s_waitcnt lgkmcnt(2)
	v_mfma_f32_16x16x32_bf16 v[54:57], v[126:129], v[98:101], v[54:57]
	v_add_f32_e32 v0, v186, v0
	v_add_f32_e32 v2, v173, v2
	v_mfma_f32_16x16x32_bf16 v[38:41], v[126:129], v[102:105], v[38:41]
	v_add_f32_e32 v0, v185, v0
	v_add_f32_e32 v2, v174, v2
	s_waitcnt lgkmcnt(1)
	v_mfma_f32_16x16x32_bf16 v[50:53], v[202:205], v[98:101], v[50:53]
	v_add_f32_e32 v0, v184, v0
	v_add_f32_e32 v2, v175, v2
	v_mfma_f32_16x16x32_bf16 v[34:37], v[202:205], v[102:105], v[34:37]
	v_add_f32_e32 v0, v183, v0
	v_add_f32_e32 v2, v176, v2
	s_waitcnt lgkmcnt(0)
	v_mfma_f32_16x16x32_bf16 v[46:49], v[210:213], v[98:101], v[46:49]
	v_add_f32_e32 v0, v182, v0
	v_add_f32_e32 v2, v177, v2
	v_mfma_f32_16x16x32_bf16 v[30:33], v[210:213], v[102:105], v[30:33]
	v_add_f32_e32 v0, v181, v0
	v_add_f32_e32 v2, v178, v2
	v_add_f32_e32 v163, v163, v0
	v_add_f32_e32 v162, v162, v2
.LBB0_887:
.LBB0_888:
	s_cmp_gt_i32 s43, -1
	s_cselect_b64 s[36:37], -1, 0
	s_cmp_lt_i32 s43, 0
	s_cbranch_scc1 .LBB0_890
	s_mul_i32 s40, s44, 0x2400
	s_addk_i32 s40, 0x2400
	s_cmp_lg_u32 s44, 2
	s_cselect_b32 s40, s40, 0
	v_lshl_add_u32 v0, s40, 1, v154
	s_waitcnt vmcnt(1)
	ds_write_b128 v0, v[24:27]
	s_waitcnt vmcnt(0)
	ds_write_b128 v0, v[62:65] offset:9216

; DI uint2 pk4(float a, float b, float c, float d) { uint2 o; o.x = pk2(a, b); o.y = pk2(c, d); return o; }
; template <class F>
; DI void epi256(int wv0, f32x4 (&acc)[2][2][4][2], int brow, int bcol, F f) {
;   const int lane = my_tid(wv0) & 63, wr = wv0 >> 2, wc = wv0 & 3;
; #pragma unroll
;   for (int ai = 0; ai < 2; ++ai)
; #pragma unroll
;     for (int bj = 0; bj < 2; ++bj)
; #pragma unroll
;       for (int m = 0; m < 4; ++m)
; #pragma unroll
;         for (int n = 0; n < 2; ++n) {
;           const int row = brow + ai * 128 + wr * 64 + m * 16 + (lane & 15);
;           const int col0 = bcol + bj * 128 + wc * 32 + n * 16 + (lane >> 4) * 4;
;           f(ai, bj, m, n, row, col0, acc[ai][bj][m][n]);
;           if (n == 1 && (m & 1)) __builtin_amdgcn_sched_barrier(0);
;         }
; DI void phaseH(int wv0, PP p, unsigned char* smem) {
;     ...
;     epi256(wv0, acc, brow, bcol, [&](int ai, int bj, int m, int n, int row, int col0, f32x4& v) {
;       const float ri = sR[row - brow];
;       const float a0 = fmaxf(v[0] * ri, 0.f), a1 = fmaxf(v[1] * ri, 0.f), a2 = fmaxf(v[2] * ri, 0.f), a3 = fmaxf(v[3] * ri, 0.f);
;       *(uint2*)(ACT + (size_t)row * 4096 + col0) = pk4(a0 * a0, a1 * a1, a2 * a2, a3 * a3);
.LBB0_1133:
	v_and_b32_e32 v130, 15, v142
	v_bfe_u32 v131, v142, 4, 2
	v_add_u32_e32 v132, s51, v130
	v_lshlrev_b32_e32 v133, 2, v132
	v_add_u32_e32 v133, 0x21400, v133
	ds_read_b32 v200, v133 offset:0
	ds_read_b32 v202, v133 offset:64
	ds_read_b32 v204, v133 offset:128
	ds_read_b32 v206, v133 offset:192
	ds_read_b32 v208, v133 offset:512
	ds_read_b32 v210, v133 offset:576
	ds_read_b32 v212, v133 offset:640
	ds_read_b32 v214, v133 offset:704
	v_mul_u32_u24_e32 v134, 528, v132
	v_lshlrev_b32_e32 v135, 3, v131
	s_lshl_b32 s78, s57, 1
	v_add3_u32 v134, v134, v135, s78
	v_add_u32_e32 v134, 32, v134
	v_add_u32_e32 v136, 67584, v134
	s_waitcnt lgkmcnt(0)
	v_mul_f32_e32 v124, v124, v200
	v_mul_f32_e32 v125, v125, v200
	v_mul_f32_e32 v126, v126, v200
	v_mul_f32_e32 v127, v127, v200
	v_max_f32_e32 v124, 0, v124
	v_max_f32_e32 v125, 0, v125
	v_max_f32_e32 v126, 0, v126
	v_max_f32_e32 v127, 0, v127
	v_pk_mul_f32 v[124:125], v[124:125], v[124:125]
	v_pk_mul_f32 v[126:127], v[126:127], v[126:127]
	v_cvt_pk_bf16_f32 v124, v124, v125
	v_cvt_pk_bf16_f32 v125, v126, v127
	ds_write_b64 v134, v[124:125] offset:0
	v_mul_f32_e32 v120, v120, v200
	v_mul_f32_e32 v121, v121, v200
	v_mul_f32_e32 v122, v122, v200
	v_mul_f32_e32 v123, v123, v200
	v_max_f32_e32 v120, 0, v120
	v_max_f32_e32 v121, 0, v121
	v_max_f32_e32 v122, 0, v122
	v_max_f32_e32 v123, 0, v123
	v_pk_mul_f32 v[120:121], v[120:121], v[120:121]
	v_pk_mul_f32 v[122:123], v[122:123], v[122:123]
	v_cvt_pk_bf16_f32 v120, v120, v121
	v_cvt_pk_bf16_f32 v121, v122, v123
	ds_write_b64 v134, v[120:121] offset:32
	v_mul_f32_e32 v116, v116, v202
	v_mul_f32_e32 v117, v117, v202
	v_mul_f32_e32 v118, v118, v202
	v_mul_f32_e32 v119, v119, v202
	v_max_f32_e32 v116, 0, v116
	v_max_f32_e32 v117, 0, v117
	v_max_f32_e32 v118, 0, v118
	v_max_f32_e32 v119, 0, v119
	v_pk_mul_f32 v[116:117], v[116:117], v[116:117]
	v_pk_mul_f32 v[118:119], v[118:119], v[118:119]
	v_cvt_pk_bf16_f32 v116, v116, v117
	v_cvt_pk_bf16_f32 v117, v118, v119
	ds_write_b64 v134, v[116:117] offset:8448
	v_mul_f32_e32 v112, v112, v202
	v_mul_f32_e32 v113, v113, v202
	v_mul_f32_e32 v114, v114, v202
	v_mul_f32_e32 v115, v115, v202
	v_max_f32_e32 v112, 0, v112
	v_max_f32_e32 v113, 0, v113
	v_max_f32_e32 v114, 0, v114
	v_max_f32_e32 v115, 0, v115
	v_pk_mul_f32 v[112:113], v[112:113], v[112:113]
	v_pk_mul_f32 v[114:115], v[114:115], v[114:115]
	v_cvt_pk_bf16_f32 v112, v112, v113
	v_cvt_pk_bf16_f32 v113, v114, v115
	ds_write_b64 v134, v[112:113] offset:8480
	v_mul_f32_e32 v108, v108, v204
	v_mul_f32_e32 v109, v109, v204
	v_mul_f32_e32 v110, v110, v204
	v_mul_f32_e32 v111, v111, v204
	v_max_f32_e32 v108, 0, v108
	v_max_f32_e32 v109, 0, v109
	v_max_f32_e32 v110, 0, v110
	v_max_f32_e32 v111, 0, v111
	v_pk_mul_f32 v[108:109], v[108:109], v[108:109]
	v_pk_mul_f32 v[110:111], v[110:111], v[110:111]
	v_cvt_pk_bf16_f32 v108, v108, v109
	v_cvt_pk_bf16_f32 v109, v110, v111
	ds_write_b64 v134, v[108:109] offset:16896
	v_mul_f32_e32 v104, v104, v204
	v_mul_f32_e32 v105, v105, v204
	v_mul_f32_e32 v106, v106, v204
	v_mul_f32_e32 v107, v107, v204
	v_max_f32_e32 v104, 0, v104
	v_max_f32_e32 v105, 0, v105
	v_max_f32_e32 v106, 0, v106
	v_max_f32_e32 v107, 0, v107
	v_pk_mul_f32 v[104:105], v[104:105], v[104:105]
	v_pk_mul_f32 v[106:107], v[106:107], v[106:107]
	v_cvt_pk_bf16_f32 v104, v104, v105
	v_cvt_pk_bf16_f32 v105, v106, v107
	ds_write_b64 v134, v[104:105] offset:16928
	v_mul_f32_e32 v100, v100, v206
	v_mul_f32_e32 v101, v101, v206
	v_mul_f32_e32 v102, v102, v206
	v_mul_f32_e32 v103, v103, v206
	v_max_f32_e32 v100, 0, v100
	v_max_f32_e32 v101, 0, v101
	v_max_f32_e32 v102, 0, v102
	v_max_f32_e32 v103, 0, v103
	v_pk_mul_f32 v[100:101], v[100:101], v[100:101]
	v_pk_mul_f32 v[102:103], v[102:103], v[102:103]
	v_cvt_pk_bf16_f32 v100, v100, v101
	v_cvt_pk_bf16_f32 v101, v102, v103
	ds_write_b64 v134, v[100:101] offset:25344
	v_mul_f32_e32 v96, v96, v206
	v_mul_f32_e32 v97, v97, v206
	v_mul_f32_e32 v98, v98, v206
	v_mul_f32_e32 v99, v99, v206
	v_max_f32_e32 v96, 0, v96
	v_max_f32_e32 v97, 0, v97
	v_max_f32_e32 v98, 0, v98
	v_max_f32_e32 v99, 0, v99
	v_pk_mul_f32 v[96:97], v[96:97], v[96:97]
	v_pk_mul_f32 v[98:99], v[98:99], v[98:99]
	v_cvt_pk_bf16_f32 v96, v96, v97
	v_cvt_pk_bf16_f32 v97, v98, v99
	ds_write_b64 v134, v[96:97] offset:25376
	v_mul_f32_e32 v92, v92, v200
	v_mul_f32_e32 v93, v93, v200
	v_mul_f32_e32 v94, v94, v200
	v_mul_f32_e32 v95, v95, v200
	v_max_f32_e32 v92, 0, v92
	v_max_f32_e32 v93, 0, v93
	v_max_f32_e32 v94, 0, v94
	v_max_f32_e32 v95, 0, v95
	v_pk_mul_f32 v[92:93], v[92:93], v[92:93]
	v_pk_mul_f32 v[94:95], v[94:95], v[94:95]
	v_cvt_pk_bf16_f32 v92, v92, v93
	v_cvt_pk_bf16_f32 v93, v94, v95
	ds_write_b64 v134, v[92:93] offset:256
	v_mul_f32_e32 v88, v88, v200
	v_mul_f32_e32 v89, v89, v200
	v_mul_f32_e32 v90, v90, v200
	v_mul_f32_e32 v91, v91, v200
	v_max_f32_e32 v88, 0, v88
	v_max_f32_e32 v89, 0, v89
	v_max_f32_e32 v90, 0, v90
	v_max_f32_e32 v91, 0, v91
	v_pk_mul_f32 v[88:89], v[88:89], v[88:89]
	v_pk_mul_f32 v[90:91], v[90:91], v[90:91]
	v_cvt_pk_bf16_f32 v88, v88, v89
	v_cvt_pk_bf16_f32 v89, v90, v91
	ds_write_b64 v134, v[88:89] offset:288
	v_mul_f32_e32 v84, v84, v202
	v_mul_f32_e32 v85, v85, v202
	v_mul_f32_e32 v86, v86, v202
	v_mul_f32_e32 v87, v87, v202
	v_max_f32_e32 v84, 0, v84
	v_max_f32_e32 v85, 0, v85
	v_max_f32_e32 v86, 0, v86
	v_max_f32_e32 v87, 0, v87
	v_pk_mul_f32 v[84:85], v[84:85], v[84:85]
	v_pk_mul_f32 v[86:87], v[86:87], v[86:87]
	v_cvt_pk_bf16_f32 v84, v84, v85
	v_cvt_pk_bf16_f32 v85, v86, v87
	ds_write_b64 v134, v[84:85] offset:8704
	v_mul_f32_e32 v80, v80, v202
	v_mul_f32_e32 v81, v81, v202
	v_mul_f32_e32 v82, v82, v202
; DI uint2 pk4(float a, float b, float c, float d) { uint2 o; o.x = pk2(a, b); o.y = pk2(c, d); return o; }
; DI void phaseH(int wv0, PP p, unsigned char* smem) {
;     ...
;     epi256(wv0, acc, brow, bcol, [&](int ai, int bj, int m, int n, int row, int col0, f32x4& v) {
;       const float ri = sR[row - brow];
;       const float a0 = fmaxf(v[0] * ri, 0.f), a1 = fmaxf(v[1] * ri, 0.f), a2 = fmaxf(v[2] * ri, 0.f), a3 = fmaxf(v[3] * ri, 0.f);
;       *(uint2*)(ACT + (size_t)row * 4096 + col0) = pk4(a0 * a0, a1 * a1, a2 * a2, a3 * a3);
	v_mul_f32_e32 v83, v83, v202
	v_max_f32_e32 v80, 0, v80
	v_max_f32_e32 v81, 0, v81
	v_max_f32_e32 v82, 0, v82
	v_max_f32_e32 v83, 0, v83
	v_pk_mul_f32 v[80:81], v[80:81], v[80:81]
	v_pk_mul_f32 v[82:83], v[82:83], v[82:83]
	v_cvt_pk_bf16_f32 v80, v80, v81
	v_cvt_pk_bf16_f32 v81, v82, v83
	ds_write_b64 v134, v[80:81] offset:8736
	v_mul_f32_e32 v76, v76, v204
	v_mul_f32_e32 v77, v77, v204
	v_mul_f32_e32 v78, v78, v204
	v_mul_f32_e32 v79, v79, v204
	v_max_f32_e32 v76, 0, v76
	v_max_f32_e32 v77, 0, v77
	v_max_f32_e32 v78, 0, v78
	v_max_f32_e32 v79, 0, v79
	v_pk_mul_f32 v[76:77], v[76:77], v[76:77]
	v_pk_mul_f32 v[78:79], v[78:79], v[78:79]
	v_cvt_pk_bf16_f32 v76, v76, v77
	v_cvt_pk_bf16_f32 v77, v78, v79
	ds_write_b64 v134, v[76:77] offset:17152
	v_mul_f32_e32 v72, v72, v204
	v_mul_f32_e32 v73, v73, v204
	v_mul_f32_e32 v74, v74, v204
	v_mul_f32_e32 v75, v75, v204
	v_max_f32_e32 v72, 0, v72
	v_max_f32_e32 v73, 0, v73
	v_max_f32_e32 v74, 0, v74
	v_max_f32_e32 v75, 0, v75
	v_pk_mul_f32 v[72:73], v[72:73], v[72:73]
	v_pk_mul_f32 v[74:75], v[74:75], v[74:75]
	v_cvt_pk_bf16_f32 v72, v72, v73
	v_cvt_pk_bf16_f32 v73, v74, v75
	ds_write_b64 v134, v[72:73] offset:17184
	v_mul_f32_e32 v68, v68, v206
	v_mul_f32_e32 v69, v69, v206
	v_mul_f32_e32 v70, v70, v206
	v_mul_f32_e32 v71, v71, v206
	v_max_f32_e32 v68, 0, v68
	v_max_f32_e32 v69, 0, v69
	v_max_f32_e32 v70, 0, v70
	v_max_f32_e32 v71, 0, v71
	v_pk_mul_f32 v[68:69], v[68:69], v[68:69]
	v_pk_mul_f32 v[70:71], v[70:71], v[70:71]
	v_cvt_pk_bf16_f32 v68, v68, v69
	v_cvt_pk_bf16_f32 v69, v70, v71
	ds_write_b64 v134, v[68:69] offset:25600
	v_mul_f32_e32 v64, v64, v206
	v_mul_f32_e32 v65, v65, v206
	v_mul_f32_e32 v66, v66, v206
	v_mul_f32_e32 v67, v67, v206
	v_max_f32_e32 v64, 0, v64
	v_max_f32_e32 v65, 0, v65
	v_max_f32_e32 v66, 0, v66
	v_max_f32_e32 v67, 0, v67
	v_pk_mul_f32 v[64:65], v[64:65], v[64:65]
	v_pk_mul_f32 v[66:67], v[66:67], v[66:67]
	v_cvt_pk_bf16_f32 v64, v64, v65
	v_cvt_pk_bf16_f32 v65, v66, v67
	ds_write_b64 v134, v[64:65] offset:25632
	v_mul_f32_e32 v60, v60, v208
	v_mul_f32_e32 v61, v61, v208
	v_mul_f32_e32 v62, v62, v208
	v_mul_f32_e32 v63, v63, v208
	v_max_f32_e32 v60, 0, v60
	v_max_f32_e32 v61, 0, v61
	v_max_f32_e32 v62, 0, v62
	v_max_f32_e32 v63, 0, v63
	v_pk_mul_f32 v[60:61], v[60:61], v[60:61]
	v_pk_mul_f32 v[62:63], v[62:63], v[62:63]
	v_cvt_pk_bf16_f32 v60, v60, v61
	v_cvt_pk_bf16_f32 v61, v62, v63
	ds_write_b64 v136, v[60:61] offset:0
	v_mul_f32_e32 v56, v56, v208
	v_mul_f32_e32 v57, v57, v208
	v_mul_f32_e32 v58, v58, v208
	v_mul_f32_e32 v59, v59, v208
	v_max_f32_e32 v56, 0, v56
	v_max_f32_e32 v57, 0, v57
	v_max_f32_e32 v58, 0, v58
	v_max_f32_e32 v59, 0, v59
	v_pk_mul_f32 v[56:57], v[56:57], v[56:57]
	v_pk_mul_f32 v[58:59], v[58:59], v[58:59]
	v_cvt_pk_bf16_f32 v56, v56, v57
	v_cvt_pk_bf16_f32 v57, v58, v59
	ds_write_b64 v136, v[56:57] offset:32
	v_mul_f32_e32 v52, v52, v210
	v_mul_f32_e32 v53, v53, v210
	v_mul_f32_e32 v54, v54, v210
	v_mul_f32_e32 v55, v55, v210
	v_max_f32_e32 v52, 0, v52
	v_max_f32_e32 v53, 0, v53
	v_max_f32_e32 v54, 0, v54
	v_max_f32_e32 v55, 0, v55
	v_pk_mul_f32 v[52:53], v[52:53], v[52:53]
	v_pk_mul_f32 v[54:55], v[54:55], v[54:55]
	v_cvt_pk_bf16_f32 v52, v52, v53
	v_cvt_pk_bf16_f32 v53, v54, v55
	ds_write_b64 v136, v[52:53] offset:8448
	v_mul_f32_e32 v48, v48, v210
	v_mul_f32_e32 v49, v49, v210
	v_mul_f32_e32 v50, v50, v210
	v_mul_f32_e32 v51, v51, v210
	v_max_f32_e32 v48, 0, v48
	v_max_f32_e32 v49, 0, v49
	v_max_f32_e32 v50, 0, v50
	v_max_f32_e32 v51, 0, v51
	v_pk_mul_f32 v[48:49], v[48:49], v[48:49]
	v_pk_mul_f32 v[50:51], v[50:51], v[50:51]
	v_cvt_pk_bf16_f32 v48, v48, v49
	v_cvt_pk_bf16_f32 v49, v50, v51
	ds_write_b64 v136, v[48:49] offset:8480
	v_mul_f32_e32 v44, v44, v212
	v_mul_f32_e32 v45, v45, v212
	v_mul_f32_e32 v46, v46, v212
	v_mul_f32_e32 v47, v47, v212
	v_max_f32_e32 v44, 0, v44
	v_max_f32_e32 v45, 0, v45
	v_max_f32_e32 v46, 0, v46
	v_max_f32_e32 v47, 0, v47
	v_pk_mul_f32 v[44:45], v[44:45], v[44:45]
	v_pk_mul_f32 v[46:47], v[46:47], v[46:47]
	v_cvt_pk_bf16_f32 v44, v44, v45
	v_cvt_pk_bf16_f32 v45, v46, v47
	ds_write_b64 v136, v[44:45] offset:16896
	v_mul_f32_e32 v40, v40, v212
	v_mul_f32_e32 v41, v41, v212
	v_mul_f32_e32 v42, v42, v212
	v_mul_f32_e32 v43, v43, v212
	v_max_f32_e32 v40, 0, v40
	v_max_f32_e32 v41, 0, v41
	v_max_f32_e32 v42, 0, v42
	v_max_f32_e32 v43, 0, v43
	v_pk_mul_f32 v[40:41], v[40:41], v[40:41]
	v_pk_mul_f32 v[42:43], v[42:43], v[42:43]
	v_cvt_pk_bf16_f32 v40, v40, v41
	v_cvt_pk_bf16_f32 v41, v42, v43
	ds_write_b64 v136, v[40:41] offset:16928
	v_mul_f32_e32 v36, v36, v214
	v_mul_f32_e32 v37, v37, v214
	v_mul_f32_e32 v38, v38, v214
	v_mul_f32_e32 v39, v39, v214
	v_max_f32_e32 v36, 0, v36
	v_max_f32_e32 v37, 0, v37
	v_max_f32_e32 v38, 0, v38
	v_max_f32_e32 v39, 0, v39
	v_pk_mul_f32 v[36:37], v[36:37], v[36:37]
	v_pk_mul_f32 v[38:39], v[38:39], v[38:39]
	v_cvt_pk_bf16_f32 v36, v36, v37
	v_cvt_pk_bf16_f32 v37, v38, v39
	ds_write_b64 v136, v[36:37] offset:25344
	v_mul_f32_e32 v32, v32, v214
	v_mul_f32_e32 v33, v33, v214
	v_mul_f32_e32 v34, v34, v214
	v_mul_f32_e32 v35, v35, v214
	v_max_f32_e32 v32, 0, v32
	v_max_f32_e32 v33, 0, v33
	v_max_f32_e32 v34, 0, v34
	v_max_f32_e32 v35, 0, v35
	v_pk_mul_f32 v[32:33], v[32:33], v[32:33]
	v_pk_mul_f32 v[34:35], v[34:35], v[34:35]
	v_cvt_pk_bf16_f32 v32, v32, v33
	v_cvt_pk_bf16_f32 v33, v34, v35
	ds_write_b64 v136, v[32:33] offset:25376
	v_mul_f32_e32 v28, v28, v208
	v_mul_f32_e32 v29, v29, v208
	v_mul_f32_e32 v30, v30, v208
	v_mul_f32_e32 v31, v31, v208
	v_max_f32_e32 v28, 0, v28
	v_max_f32_e32 v29, 0, v29
	v_max_f32_e32 v30, 0, v30
	v_max_f32_e32 v31, 0, v31
	v_pk_mul_f32 v[28:29], v[28:29], v[28:29]
; DI uint2 pk4(float a, float b, float c, float d) { uint2 o; o.x = pk2(a, b); o.y = pk2(c, d); return o; }
; DI void phaseH(int wv0, PP p, unsigned char* smem) {
;     ...
;     epi256(wv0, acc, brow, bcol, [&](int ai, int bj, int m, int n, int row, int col0, f32x4& v) {
;       const float ri = sR[row - brow];
;       const float a0 = fmaxf(v[0] * ri, 0.f), a1 = fmaxf(v[1] * ri, 0.f), a2 = fmaxf(v[2] * ri, 0.f), a3 = fmaxf(v[3] * ri, 0.f);
;       *(uint2*)(ACT + (size_t)row * 4096 + col0) = pk4(a0 * a0, a1 * a1, a2 * a2, a3 * a3);
;     });
;     __syncthreads();
;   }
	v_pk_mul_f32 v[30:31], v[30:31], v[30:31]
	v_cvt_pk_bf16_f32 v28, v28, v29
	v_cvt_pk_bf16_f32 v29, v30, v31
	ds_write_b64 v136, v[28:29] offset:256
	v_mul_f32_e32 v24, v24, v208
	v_mul_f32_e32 v25, v25, v208
	v_mul_f32_e32 v26, v26, v208
	v_mul_f32_e32 v27, v27, v208
	v_max_f32_e32 v24, 0, v24
	v_max_f32_e32 v25, 0, v25
	v_max_f32_e32 v26, 0, v26
	v_max_f32_e32 v27, 0, v27
	v_pk_mul_f32 v[24:25], v[24:25], v[24:25]
	v_pk_mul_f32 v[26:27], v[26:27], v[26:27]
	v_cvt_pk_bf16_f32 v24, v24, v25
	v_cvt_pk_bf16_f32 v25, v26, v27
	ds_write_b64 v136, v[24:25] offset:288
	v_mul_f32_e32 v20, v20, v210
	v_mul_f32_e32 v21, v21, v210
	v_mul_f32_e32 v22, v22, v210
	v_mul_f32_e32 v23, v23, v210
	v_max_f32_e32 v20, 0, v20
	v_max_f32_e32 v21, 0, v21
	v_max_f32_e32 v22, 0, v22
	v_max_f32_e32 v23, 0, v23
	v_pk_mul_f32 v[20:21], v[20:21], v[20:21]
	v_pk_mul_f32 v[22:23], v[22:23], v[22:23]
	v_cvt_pk_bf16_f32 v20, v20, v21
	v_cvt_pk_bf16_f32 v21, v22, v23
	ds_write_b64 v136, v[20:21] offset:8704
	v_mul_f32_e32 v16, v16, v210
	v_mul_f32_e32 v17, v17, v210
	v_mul_f32_e32 v18, v18, v210
	v_mul_f32_e32 v19, v19, v210
	v_max_f32_e32 v16, 0, v16
	v_max_f32_e32 v17, 0, v17
	v_max_f32_e32 v18, 0, v18
	v_max_f32_e32 v19, 0, v19
	v_pk_mul_f32 v[16:17], v[16:17], v[16:17]
	v_pk_mul_f32 v[18:19], v[18:19], v[18:19]
	v_cvt_pk_bf16_f32 v16, v16, v17
	v_cvt_pk_bf16_f32 v17, v18, v19
	ds_write_b64 v136, v[16:17] offset:8736
	v_mul_f32_e32 v12, v12, v212
	v_mul_f32_e32 v13, v13, v212
	v_mul_f32_e32 v14, v14, v212
	v_mul_f32_e32 v15, v15, v212
	v_max_f32_e32 v12, 0, v12
	v_max_f32_e32 v13, 0, v13
	v_max_f32_e32 v14, 0, v14
	v_max_f32_e32 v15, 0, v15
	v_pk_mul_f32 v[12:13], v[12:13], v[12:13]
	v_pk_mul_f32 v[14:15], v[14:15], v[14:15]
	v_cvt_pk_bf16_f32 v12, v12, v13
	v_cvt_pk_bf16_f32 v13, v14, v15
	ds_write_b64 v136, v[12:13] offset:17152
	v_mul_f32_e32 v8, v8, v212
	v_mul_f32_e32 v9, v9, v212
	v_mul_f32_e32 v10, v10, v212
	v_mul_f32_e32 v11, v11, v212
	v_max_f32_e32 v8, 0, v8
	v_max_f32_e32 v9, 0, v9
	v_max_f32_e32 v10, 0, v10
	v_max_f32_e32 v11, 0, v11
	v_pk_mul_f32 v[8:9], v[8:9], v[8:9]
	v_pk_mul_f32 v[10:11], v[10:11], v[10:11]
	v_cvt_pk_bf16_f32 v8, v8, v9
	v_cvt_pk_bf16_f32 v9, v10, v11
	ds_write_b64 v136, v[8:9] offset:17184
	v_mul_f32_e32 v4, v4, v214
	v_mul_f32_e32 v5, v5, v214
	v_mul_f32_e32 v6, v6, v214
	v_mul_f32_e32 v7, v7, v214
	v_max_f32_e32 v4, 0, v4
	v_max_f32_e32 v5, 0, v5
	v_max_f32_e32 v6, 0, v6
	v_max_f32_e32 v7, 0, v7
	v_pk_mul_f32 v[4:5], v[4:5], v[4:5]
	v_pk_mul_f32 v[6:7], v[6:7], v[6:7]
	v_cvt_pk_bf16_f32 v4, v4, v5
	v_cvt_pk_bf16_f32 v5, v6, v7
	ds_write_b64 v136, v[4:5] offset:25600
	v_mul_f32_e32 v0, v0, v214
	v_mul_f32_e32 v1, v1, v214
	v_mul_f32_e32 v2, v2, v214
	v_mul_f32_e32 v3, v3, v214
	v_max_f32_e32 v0, 0, v0
	v_max_f32_e32 v1, 0, v1
	v_max_f32_e32 v2, 0, v2
	v_max_f32_e32 v3, 0, v3
	v_pk_mul_f32 v[0:1], v[0:1], v[0:1]
	v_pk_mul_f32 v[2:3], v[2:3], v[2:3]
	v_cvt_pk_bf16_f32 v0, v0, v1
	v_cvt_pk_bf16_f32 v1, v2, v3
	ds_write_b64 v136, v[0:1] offset:25632
	s_waitcnt lgkmcnt(0)
	s_barrier
	v_and_b32_e32 v137, 63, v142
	v_lshrrev_b32_e32 v138, 5, v137
	v_and_b32_e32 v137, 31, v137
	s_lshl_b32 s79, s89, 5
	v_add_u32_e32 v138, s79, v138
	v_mul_u32_u24_e32 v139, 528, v138
	v_lshl_add_u32 v139, v137, 4, v139
	v_add_u32_e32 v139, 32, v139
	v_add_u32_e32 v140, s46, v138
	v_lshlrev_b32_e32 v140, 13, v140
	v_lshl_add_u32 v140, v137, 4, v140
	s_lshl_b32 s79, s48, 9
	v_add_u32_e32 v140, s79, v140
	ds_read_b128 v[0:3], v139 offset:0
	ds_read_b128 v[4:7], v139 offset:1056
	ds_read_b128 v[8:11], v139 offset:2112
	ds_read_b128 v[12:15], v139 offset:3168
	ds_read_b128 v[16:19], v139 offset:4224
	ds_read_b128 v[20:23], v139 offset:5280
	ds_read_b128 v[24:27], v139 offset:6336
	ds_read_b128 v[28:31], v139 offset:7392
	ds_read_b128 v[32:35], v139 offset:8448
	ds_read_b128 v[36:39], v139 offset:9504
	ds_read_b128 v[40:43], v139 offset:10560
	ds_read_b128 v[44:47], v139 offset:11616
	ds_read_b128 v[48:51], v139 offset:12672
	ds_read_b128 v[52:55], v139 offset:13728
	ds_read_b128 v[56:59], v139 offset:14784
	ds_read_b128 v[60:63], v139 offset:15840
	v_add_u32_e32 v217, 0x4000, v140
	v_add_u32_e32 v218, 0x8000, v140
	v_add_u32_e32 v219, 0xc000, v140
	v_add_u32_e32 v220, 0x10000, v140
	v_add_u32_e32 v221, 0x14000, v140
	v_add_u32_e32 v222, 0x18000, v140
	v_add_u32_e32 v223, 0x1c000, v140
	v_add_u32_e32 v224, 0x20000, v140
	v_add_u32_e32 v225, 0x24000, v140
	v_add_u32_e32 v226, 0x28000, v140
	v_add_u32_e32 v227, 0x2c000, v140
	v_add_u32_e32 v228, 0x30000, v140
	v_add_u32_e32 v229, 0x34000, v140
	v_add_u32_e32 v230, 0x38000, v140
	v_add_u32_e32 v231, 0x3c000, v140
	s_waitcnt lgkmcnt(15)
	global_store_dwordx4 v140, v[0:3], s[10:11]
	s_waitcnt lgkmcnt(14)
	global_store_dwordx4 v217, v[4:7], s[10:11]
	s_waitcnt lgkmcnt(13)
	global_store_dwordx4 v218, v[8:11], s[10:11]
	s_waitcnt lgkmcnt(12)
	global_store_dwordx4 v219, v[12:15], s[10:11]
	s_waitcnt lgkmcnt(11)
	global_store_dwordx4 v220, v[16:19], s[10:11]
	s_waitcnt lgkmcnt(10)
	global_store_dwordx4 v221, v[20:23], s[10:11]
	s_waitcnt lgkmcnt(9)
	global_store_dwordx4 v222, v[24:27], s[10:11]
	s_waitcnt lgkmcnt(8)
	global_store_dwordx4 v223, v[28:31], s[10:11]
	s_waitcnt lgkmcnt(7)
	global_store_dwordx4 v224, v[32:35], s[10:11]
	s_waitcnt lgkmcnt(6)
	global_store_dwordx4 v225, v[36:39], s[10:11]
	s_waitcnt lgkmcnt(5)
	global_store_dwordx4 v226, v[40:43], s[10:11]
	s_waitcnt lgkmcnt(4)
	global_store_dwordx4 v227, v[44:47], s[10:11]
	s_waitcnt lgkmcnt(3)
	global_store_dwordx4 v228, v[48:51], s[10:11]
	s_waitcnt lgkmcnt(2)
	global_store_dwordx4 v229, v[52:55], s[10:11]
	s_waitcnt lgkmcnt(1)
	global_store_dwordx4 v230, v[56:59], s[10:11]
	s_waitcnt lgkmcnt(0)
	global_store_dwordx4 v231, v[60:63], s[10:11]
	s_waitcnt vmcnt(0)
	s_barrier
	s_load_dword s4, s[16:17], 0x0
	s_waitcnt lgkmcnt(0)
	s_add_i32 s67, s4, s67
	s_cmpk_lt_i32 s67, 0x800
	s_cbranch_scc0 .LBB0_1142
; DI void phaseH(int wv0, PP p, unsigned char* smem) {
;     ...
;   for (int id = blockIdx.x; id < 128 * 16; id += gridDim.x) {
;     int pm, pn;
;     tile_map_n16(id, pm, pn);
;     const int brow = pm * 256, bcol = pn * 256;
;     const int tid = my_tid(wv0);
;     if (tid < 256) {
;       const float4* s = (const float4*)(SS1 + (size_t)(brow + tid) * 16);
;       const float4 a = s[0], b = s[1], c = s[2], d = s[3];
;       const float t = a.x + a.y + a.z + a.w + b.x + b.y + b.z + b.w + c.x + c.y + c.z + c.w + d.x + d.y + d.z + d.w;
;       sR[tid] = rsqrtf(t * (1.f / 1024.f) + 1e-6f);
;     }
.LBB0_1134:
	s_ashr_i32 s4, s67, 4
	s_and_b32 s68, s4, -16
	s_lshl_b32 s4, s67, 1
	s_and_b32 s69, s4, 12
	s_or_b32 s4, s68, s69
	s_bfe_u32 s70, s67, 0x20006
	s_or_b32 s4, s4, s70
	v_mov_b32_e32 v0, v142
	s_lshl_b32 s46, s4, 8
	s_nop 0
	v_cmp_gt_i32_e32 vcc, s55, v0
	s_and_saveexec_b64 s[48:49], vcc
	s_cbranch_execz .LBB0_1136
	v_add_u32_e32 v2, s46, v0
	v_ashrrev_i32_e32 v3, 31, v2
	v_lshlrev_b64 v[2:3], 6, v[2:3]
	v_lshl_add_u64 v[14:15], s[8:9], 0, v[2:3]
	global_load_dwordx4 v[2:5], v[14:15], off
	global_load_dwordx4 v[6:9], v[14:15], off offset:16
	global_load_dwordx4 v[10:13], v[14:15], off offset:32
	s_nop 0
	global_load_dwordx4 v[14:17], v[14:15], off offset:48
	v_lshl_add_u32 v0, v0, 2, 32
	v_add_u32_e32 v0, 0x213e0, v0
	s_waitcnt vmcnt(0)
	v_add_f32_e32 v1, v2, v3
	v_add_f32_e32 v1, v1, v4
	v_add_f32_e32 v1, v1, v5
	v_add_f32_e32 v1, v1, v6
	v_add_f32_e32 v1, v1, v7
	v_add_f32_e32 v1, v1, v8
	v_add_f32_e32 v1, v1, v9
	v_add_f32_e32 v1, v1, v10
	v_add_f32_e32 v1, v1, v11
	v_add_f32_e32 v1, v1, v12
	v_add_f32_e32 v1, v1, v13
	v_add_f32_e32 v1, v1, v14
	v_add_f32_e32 v1, v1, v15
	v_add_f32_e32 v1, v1, v16
	v_add_f32_e32 v1, v1, v17
	v_fmamk_f32 v1, v1, 0x3a800000, v143
	v_mul_f32_e32 v2, 0x4b800000, v1
	v_cmp_gt_f32_e32 vcc, s66, v1
	s_nop 1
	v_cndmask_b32_e32 v1, v1, v2, vcc
	v_rsq_f32_e32 v1, v1
	s_nop 0
	v_mul_f32_e32 v2, 0x45800000, v1
	v_cndmask_b32_e32 v1, v1, v2, vcc
	ds_write_b32 v0, v1

; __global__ void __launch_bounds__(512, 2) mega(Params p) {
;   extern __shared__ __attribute__((aligned(16))) unsigned char smem[];
;   const int wv0 = __builtin_amdgcn_readfirstlane((int)(threadIdx.x >> 6));
	.amdhsa_kernel _Z4mega6Params
		.amdhsa_group_segment_fixed_size 5152
		.amdhsa_private_segment_fixed_size 0
		.amdhsa_kernarg_size 472
		.amdhsa_user_sgpr_count 2
		.amdhsa_user_sgpr_dispatch_ptr 0
		.amdhsa_user_sgpr_queue_ptr 0
		.amdhsa_user_sgpr_kernarg_segment_ptr 1
		.amdhsa_user_sgpr_dispatch_id 0
		.amdhsa_user_sgpr_kernarg_preload_length 0
		.amdhsa_user_sgpr_kernarg_preload_offset 0
		.amdhsa_user_sgpr_private_segment_size 0
		.amdhsa_uses_dynamic_stack 0
		.amdhsa_enable_private_segment 0
		.amdhsa_system_sgpr_workgroup_id_x 1
		.amdhsa_system_sgpr_workgroup_id_y 0
		.amdhsa_system_sgpr_workgroup_id_z 0
		.amdhsa_system_sgpr_workgroup_info 0
		.amdhsa_system_vgpr_workitem_id 2
		.amdhsa_next_free_vgpr 248
		.amdhsa_next_free_sgpr 98
		.amdhsa_accum_offset 248
		.amdhsa_reserve_vcc 1
		.amdhsa_float_round_mode_32 0
		.amdhsa_float_round_mode_16_64 0
		.amdhsa_float_denorm_mode_32 3
		.amdhsa_float_denorm_mode_16_64 3
		.amdhsa_dx10_clamp 1
		.amdhsa_ieee_mode 1
		.amdhsa_fp16_overflow 0
		.amdhsa_tg_split 0
		.amdhsa_exception_fp_ieee_invalid_op 0
		.amdhsa_exception_fp_denorm_src 0
		.amdhsa_exception_fp_ieee_div_zero 0
		.amdhsa_exception_fp_ieee_overflow 0
		.amdhsa_exception_fp_ieee_underflow 0
		.amdhsa_exception_fp_ieee_inexact 0
		.amdhsa_exception_int_div_zero 0
	.end_amdhsa_kernel

; __global__ void __launch_bounds__(512, 2) mega(Params p) {
;   extern __shared__ __attribute__((aligned(16))) unsigned char smem[];
;   const int wv0 = __builtin_amdgcn_readfirstlane((int)(threadIdx.x >> 6));
amdhsa.kernels:
  - .agpr_count:     0
    .args:
      - .offset:         0
        .size:           216
        .value_kind:     by_value
      - .offset:         216
        .size:           4
        .value_kind:     hidden_block_count_x
      - .offset:         220
        .size:           4
        .value_kind:     hidden_block_count_y
      - .offset:         224
        .size:           4
        .value_kind:     hidden_block_count_z
      - .offset:         228
        .size:           2
        .value_kind:     hidden_group_size_x
      - .offset:         230
        .size:           2
        .value_kind:     hidden_group_size_y
      - .offset:         232
        .size:           2
        .value_kind:     hidden_group_size_z
      - .offset:         234
        .size:           2
        .value_kind:     hidden_remainder_x
      - .offset:         236
        .size:           2
        .value_kind:     hidden_remainder_y
      - .offset:         238
        .size:           2
        .value_kind:     hidden_remainder_z
      - .offset:         256
        .size:           8
        .value_kind:     hidden_global_offset_x
      - .offset:         264
        .size:           8
        .value_kind:     hidden_global_offset_y
      - .offset:         272
        .size:           8
        .value_kind:     hidden_global_offset_z
      - .offset:         280
        .size:           2
        .value_kind:     hidden_grid_dims
      - .offset:         304
        .size:           8
        .value_kind:     hidden_multigrid_sync_arg
      - .offset:         336
        .size:           4
        .value_kind:     hidden_dynamic_lds_size
    .group_segment_fixed_size: 5152
    .kernarg_segment_align: 8
    .kernarg_segment_size: 472
    .language:       OpenCL C
    .language_version:
      - 2
      - 0
    .max_flat_workgroup_size: 512
    .name:           _Z4mega6Params
    .private_segment_fixed_size: 0
    .sgpr_count:     104
    .sgpr_spill_count: 86
    .symbol:         _Z4mega6Params.kd
    .uniform_work_group_size: 1
    .uses_dynamic_stack: false
    .vgpr_count:     248
    .vgpr_spill_count: 0
    .wavefront_size: 64
